# v19 plus state tile body regenerated v2: batched B-fragment reads, K^T prefetch, and 80 per-tile LDS address VALU ops replaced by 5 bases plus ds_read immediate offsets
# speedup vs baseline: 1.0060x; 1.0060x over previous
; #define LAS __attribute__((address_space(3)))
; __device__ __forceinline__ unsigned cvtpk(float lo, float hi) { f32x2 v = {lo, hi}; bf16x2_t b = __builtin_convertvector(v, bf16x2_t); return __builtin_bit_cast(unsigned, b); }
; __device__ __forceinline__ float bflo(unsigned w) { return __uint_as_float(w << 16); }
; __device__ __forceinline__ float bfhi(unsigned w) { return __uint_as_float(w & 0xffff0000u); }
; __device__ __forceinline__ s16x4 vtr(const LAS unsigned char* p) { return __builtin_bit_cast(s16x4, __builtin_amdgcn_ds_read_tr16_b64_v4i16((LAS v4i16_t*)p)); }
; #define MFMA32(a, b, c) __builtin_amdgcn_mfma_f32_32x32x16_bf16((a), (b), (c), 0, 0, 0)
; __device__ __forceinline__ void state_unit(LAS unsigned char* lds, const Args& a, int b, int hh, int dir, int eh, int wid, int lane) {
;     ...
;         const LAS unsigned char* Kt = lds + (t % 3) * 49152; const LAS unsigned char* Vt = Kt + 32768;
;         const int p0 = (t < 4 ? 64 * t : 64 * ((t - 4) % TPC)) + 8 * h, last = t < 4 ? 255 : RCH - 1;
; #pragma unroll
;         for (int s = 0; s < 4; ++s) {
;             const LAS unsigned char* kb = Kt + (16 * s + 8 * h + tq) * 512 + lanec + (((wid ^ tq) & 3) << 6) + (wid >> 2) * 256;
;             const s16x4 klo = vtr(kb), khi = vtr(kb + 4 * 512);
;             const int p = p0 + 16 * s;
;             float w = __builtin_amdgcn_exp2f(lg2 * (float)(dir ? p : last - p));
;             const u32x2 lw = __builtin_bit_cast(u32x2, klo), hw = __builtin_bit_cast(u32x2, khi);
;             float kv[8] = {bflo(lw.x), bfhi(lw.x), bflo(lw.y), bfhi(lw.y), bflo(hw.x), bfhi(hw.x), bflo(hw.y), bfhi(hw.y)};
; #pragma unroll
;             for (int j = 0; j < 8; ++j) { kv[j] *= w; w *= m; }
;             u32x4 pw; pw.x = cvtpk(kv[0], kv[1]); pw.y = cvtpk(kv[2], kv[3]); pw.z = cvtpk(kv[4], kv[5]); pw.w = cvtpk(kv[6], kv[7]);
;             const bf16x8 af = __builtin_bit_cast(bf16x8, pw);
;             const LAS unsigned char* vb = Vt + (16 * s + 8 * h + tq) * 256 + lanec;
; #pragma unroll
;             for (int d = 0; d < 4; ++d) {
;                 const LAS unsigned char* vp = vb + (((d ^ tq) & 3) << 6);
;                 const s16x4 lo = vtr(vp), hi = vtr(vp + 4 * 256);
;                 acc[d] = MFMA32(af, __builtin_shufflevector(lo, hi, 0, 1, 2, 3, 4, 5, 6, 7), acc[d]); }
;         }
.LBB0_579:
	s_mul_hi_u32 s40, s78, 0xaaaaaaab
	s_lshr_b32 s40, s40, 1
	s_mul_i32 s40, s40, 0xfffdc000
	s_add_i32 s46, s76, 0xfffffe80
	v_add_u32_e32 v183, s40, v148
	v_add3_u32 v183, v183, v141, s77
	v_add_u32_e32 v184, s40, v182
	v_add3_u32 v184, v184, v141, s77
	v_add_u32_e32 v185, s40, v180
	v_add3_u32 v185, v185, v141, s77
	v_add_u32_e32 v186, s40, v178
	v_add3_u32 v186, v186, v141, s77
	v_add_u32_e32 v187, s40, v174
	v_add3_u32 v187, v187, v141, s77
	s_and_b32 s40, s46, 0x1c0
	s_xor_b32 s47, s40, 0x100
	s_cmp_lt_u32 s79, 4
	s_movk_i32 s40, 0x1ff
	s_cselect_b32 s46, s46, s47
	s_cselect_b32 s40, 0xff, s40
	v_add_u32_e32 v195, s46, v139
	ds_read_b64_tr_b16 v[64:65], v183
	ds_read_b64_tr_b16 v[66:67], v183 offset:2048
	ds_read_b64_tr_b16 v[228:229], v184
	ds_read_b64_tr_b16 v[230:231], v184 offset:1024
	ds_read_b64_tr_b16 v[232:233], v185
	ds_read_b64_tr_b16 v[234:235], v185 offset:1024
	ds_read_b64_tr_b16 v[236:237], v186
	ds_read_b64_tr_b16 v[238:239], v186 offset:1024
	ds_read_b64_tr_b16 v[216:217], v187
	ds_read_b64_tr_b16 v[218:219], v187 offset:1024
	ds_read_b64_tr_b16 v[220:221], v183 offset:8192
	ds_read_b64_tr_b16 v[222:223], v183 offset:10240
	v_sub_u32_e32 v240, s40, v195
	v_cndmask_b32_e64 v227, v195, v240, s[0:1]
	v_cvt_f32_i32_e32 v227, v227
	v_mul_f32_e32 v227, v137, v227
	v_exp_f32_e32 v212, v227
	s_waitcnt lgkmcnt(10)
	v_lshlrev_b32_e32 v214, 16, v64
	v_and_b32_e32 v215, 0xffff0000, v64
	v_mul_f32_e32 v213, v138, v212
	v_pk_mul_f32 v[214:215], v[212:213], v[214:215]
	v_cvt_pk_bf16_f32 v64, v214, v215
	v_lshlrev_b32_e32 v214, 16, v65
	v_and_b32_e32 v215, 0xffff0000, v65
	v_mul_f32_e32 v212, v138, v213
	v_mul_f32_e32 v213, v138, v212
	v_pk_mul_f32 v[214:215], v[212:213], v[214:215]
	v_cvt_pk_bf16_f32 v65, v214, v215
	v_lshlrev_b32_e32 v214, 16, v66
	v_and_b32_e32 v215, 0xffff0000, v66
	v_mul_f32_e32 v212, v138, v213
	v_mul_f32_e32 v213, v138, v212
	v_pk_mul_f32 v[214:215], v[212:213], v[214:215]
	v_cvt_pk_bf16_f32 v66, v214, v215
	v_lshlrev_b32_e32 v214, 16, v67
	v_and_b32_e32 v215, 0xffff0000, v67
	v_mul_f32_e32 v212, v138, v213
	v_mul_f32_e32 v213, v138, v212
	v_pk_mul_f32 v[214:215], v[212:213], v[214:215]
	v_cvt_pk_bf16_f32 v67, v214, v215
	s_nop 1
	s_waitcnt lgkmcnt(8)
	v_mfma_f32_32x32x16_bf16 v[48:63], v[64:67], v[228:231], v[48:63]
	s_waitcnt lgkmcnt(6)
	v_mfma_f32_32x32x16_bf16 v[32:47], v[64:67], v[232:235], v[32:47]
	s_waitcnt lgkmcnt(4)
	v_mfma_f32_32x32x16_bf16 v[16:31], v[64:67], v[236:239], v[16:31]
	s_waitcnt lgkmcnt(2)
	v_mfma_f32_32x32x16_bf16 v[0:15], v[64:67], v[216:219], v[0:15]
	ds_read_b64_tr_b16 v[228:229], v184 offset:4096
	ds_read_b64_tr_b16 v[230:231], v184 offset:5120
	ds_read_b64_tr_b16 v[232:233], v185 offset:4096
	ds_read_b64_tr_b16 v[234:235], v185 offset:5120
	ds_read_b64_tr_b16 v[236:237], v186 offset:4096
	ds_read_b64_tr_b16 v[238:239], v186 offset:5120
	ds_read_b64_tr_b16 v[216:217], v187 offset:4096
	ds_read_b64_tr_b16 v[218:219], v187 offset:5120
	ds_read_b64_tr_b16 v[204:205], v183 offset:16384
	ds_read_b64_tr_b16 v[206:207], v183 offset:18432
	v_add_u32_e32 v227, 16, v195
	v_sub_u32_e32 v240, s40, v227
	v_cndmask_b32_e64 v227, v227, v240, s[0:1]
	v_cvt_f32_i32_e32 v227, v227
	v_mul_f32_e32 v227, v137, v227
	v_exp_f32_e32 v212, v227
	s_waitcnt lgkmcnt(10)
	v_lshlrev_b32_e32 v214, 16, v220
	v_and_b32_e32 v215, 0xffff0000, v220
	v_mul_f32_e32 v213, v138, v212
	v_pk_mul_f32 v[214:215], v[212:213], v[214:215]
	v_cvt_pk_bf16_f32 v220, v214, v215
	v_lshlrev_b32_e32 v214, 16, v221
	v_and_b32_e32 v215, 0xffff0000, v221
	v_mul_f32_e32 v212, v138, v213
	v_mul_f32_e32 v213, v138, v212
	v_pk_mul_f32 v[214:215], v[212:213], v[214:215]
	v_cvt_pk_bf16_f32 v221, v214, v215
	v_lshlrev_b32_e32 v214, 16, v222
	v_and_b32_e32 v215, 0xffff0000, v222
	v_mul_f32_e32 v212, v138, v213
	v_mul_f32_e32 v213, v138, v212
	v_pk_mul_f32 v[214:215], v[212:213], v[214:215]
	v_cvt_pk_bf16_f32 v222, v214, v215
	v_lshlrev_b32_e32 v214, 16, v223
	v_and_b32_e32 v215, 0xffff0000, v223
	v_mul_f32_e32 v212, v138, v213
	v_mul_f32_e32 v213, v138, v212
	v_pk_mul_f32 v[214:215], v[212:213], v[214:215]
	v_cvt_pk_bf16_f32 v223, v214, v215
	s_nop 1
	s_waitcnt lgkmcnt(8)
	v_mfma_f32_32x32x16_bf16 v[48:63], v[220:223], v[228:231], v[48:63]
	s_waitcnt lgkmcnt(6)
; #define LAS __attribute__((address_space(3)))
; __device__ __forceinline__ unsigned cvtpk(float lo, float hi) { f32x2 v = {lo, hi}; bf16x2_t b = __builtin_convertvector(v, bf16x2_t); return __builtin_bit_cast(unsigned, b); }
; __device__ __forceinline__ float bflo(unsigned w) { return __uint_as_float(w << 16); }
; __device__ __forceinline__ float bfhi(unsigned w) { return __uint_as_float(w & 0xffff0000u); }
; __device__ __forceinline__ s16x4 vtr(const LAS unsigned char* p) { return __builtin_bit_cast(s16x4, __builtin_amdgcn_ds_read_tr16_b64_v4i16((LAS v4i16_t*)p)); }
; #define MFMA32(a, b, c) __builtin_amdgcn_mfma_f32_32x32x16_bf16((a), (b), (c), 0, 0, 0)
; __device__ __forceinline__ void state_unit(LAS unsigned char* lds, const Args& a, int b, int hh, int dir, int eh, int wid, int lane) {
;     ...
; #pragma unroll
;         for (int s = 0; s < 4; ++s) {
;             const LAS unsigned char* kb = Kt + (16 * s + 8 * h + tq) * 512 + lanec + (((wid ^ tq) & 3) << 6) + (wid >> 2) * 256;
;             const s16x4 klo = vtr(kb), khi = vtr(kb + 4 * 512);
;             const int p = p0 + 16 * s;
;             float w = __builtin_amdgcn_exp2f(lg2 * (float)(dir ? p : last - p));
;             const u32x2 lw = __builtin_bit_cast(u32x2, klo), hw = __builtin_bit_cast(u32x2, khi);
;             float kv[8] = {bflo(lw.x), bfhi(lw.x), bflo(lw.y), bfhi(lw.y), bflo(hw.x), bfhi(hw.x), bflo(hw.y), bfhi(hw.y)};
; #pragma unroll
;             for (int j = 0; j < 8; ++j) { kv[j] *= w; w *= m; }
;             u32x4 pw; pw.x = cvtpk(kv[0], kv[1]); pw.y = cvtpk(kv[2], kv[3]); pw.z = cvtpk(kv[4], kv[5]); pw.w = cvtpk(kv[6], kv[7]);
;             const bf16x8 af = __builtin_bit_cast(bf16x8, pw);
;             const LAS unsigned char* vb = Vt + (16 * s + 8 * h + tq) * 256 + lanec;
; #pragma unroll
;             for (int d = 0; d < 4; ++d) {
;                 const LAS unsigned char* vp = vb + (((d ^ tq) & 3) << 6);
;                 const s16x4 lo = vtr(vp), hi = vtr(vp + 4 * 256);
;                 acc[d] = MFMA32(af, __builtin_shufflevector(lo, hi, 0, 1, 2, 3, 4, 5, 6, 7), acc[d]); }
;         }
	v_mfma_f32_32x32x16_bf16 v[32:47], v[220:223], v[232:235], v[32:47]
	s_waitcnt lgkmcnt(4)
	v_mfma_f32_32x32x16_bf16 v[16:31], v[220:223], v[236:239], v[16:31]
	s_waitcnt lgkmcnt(2)
	v_mfma_f32_32x32x16_bf16 v[0:15], v[220:223], v[216:219], v[0:15]
	ds_read_b64_tr_b16 v[228:229], v184 offset:8192
	ds_read_b64_tr_b16 v[230:231], v184 offset:9216
	ds_read_b64_tr_b16 v[232:233], v185 offset:8192
	ds_read_b64_tr_b16 v[234:235], v185 offset:9216
	ds_read_b64_tr_b16 v[236:237], v186 offset:8192
	ds_read_b64_tr_b16 v[238:239], v186 offset:9216
	ds_read_b64_tr_b16 v[216:217], v187 offset:8192
	ds_read_b64_tr_b16 v[218:219], v187 offset:9216
	ds_read_b64_tr_b16 v[190:191], v183 offset:24576
	ds_read_b64_tr_b16 v[192:193], v183 offset:26624
	v_add_u32_e32 v227, 32, v195
	v_sub_u32_e32 v240, s40, v227
	v_cndmask_b32_e64 v227, v227, v240, s[0:1]
	v_cvt_f32_i32_e32 v227, v227
	v_mul_f32_e32 v227, v137, v227
	v_exp_f32_e32 v212, v227
	s_waitcnt lgkmcnt(10)
	v_lshlrev_b32_e32 v214, 16, v204
	v_and_b32_e32 v215, 0xffff0000, v204
	v_mul_f32_e32 v213, v138, v212
	v_pk_mul_f32 v[214:215], v[212:213], v[214:215]
	v_cvt_pk_bf16_f32 v204, v214, v215
	v_lshlrev_b32_e32 v214, 16, v205
	v_and_b32_e32 v215, 0xffff0000, v205
	v_mul_f32_e32 v212, v138, v213
	v_mul_f32_e32 v213, v138, v212
	v_pk_mul_f32 v[214:215], v[212:213], v[214:215]
	v_cvt_pk_bf16_f32 v205, v214, v215
	v_lshlrev_b32_e32 v214, 16, v206
	v_and_b32_e32 v215, 0xffff0000, v206
	v_mul_f32_e32 v212, v138, v213
	v_mul_f32_e32 v213, v138, v212
	v_pk_mul_f32 v[214:215], v[212:213], v[214:215]
	v_cvt_pk_bf16_f32 v206, v214, v215
	v_lshlrev_b32_e32 v214, 16, v207
	v_and_b32_e32 v215, 0xffff0000, v207
	v_mul_f32_e32 v212, v138, v213
	v_mul_f32_e32 v213, v138, v212
	v_pk_mul_f32 v[214:215], v[212:213], v[214:215]
	v_cvt_pk_bf16_f32 v207, v214, v215
	s_nop 1
	s_waitcnt lgkmcnt(8)
	v_mfma_f32_32x32x16_bf16 v[48:63], v[204:207], v[228:231], v[48:63]
	s_waitcnt lgkmcnt(6)
	v_mfma_f32_32x32x16_bf16 v[32:47], v[204:207], v[232:235], v[32:47]
	s_waitcnt lgkmcnt(4)
	v_mfma_f32_32x32x16_bf16 v[16:31], v[204:207], v[236:239], v[16:31]
	s_waitcnt lgkmcnt(2)
	v_mfma_f32_32x32x16_bf16 v[0:15], v[204:207], v[216:219], v[0:15]
	ds_read_b64_tr_b16 v[228:229], v184 offset:12288
	ds_read_b64_tr_b16 v[230:231], v184 offset:13312
	ds_read_b64_tr_b16 v[232:233], v185 offset:12288
	ds_read_b64_tr_b16 v[234:235], v185 offset:13312
	ds_read_b64_tr_b16 v[236:237], v186 offset:12288
	ds_read_b64_tr_b16 v[238:239], v186 offset:13312
	ds_read_b64_tr_b16 v[216:217], v187 offset:12288
	ds_read_b64_tr_b16 v[218:219], v187 offset:13312
	v_add_u32_e32 v227, 48, v195
	v_sub_u32_e32 v240, s40, v227
	v_cndmask_b32_e64 v227, v227, v240, s[0:1]
	v_cvt_f32_i32_e32 v227, v227
	v_mul_f32_e32 v227, v137, v227
	v_exp_f32_e32 v212, v227
	s_waitcnt lgkmcnt(8)
	v_lshlrev_b32_e32 v214, 16, v190
	v_and_b32_e32 v215, 0xffff0000, v190
	v_mul_f32_e32 v213, v138, v212
	v_pk_mul_f32 v[214:215], v[212:213], v[214:215]
	v_cvt_pk_bf16_f32 v190, v214, v215
	v_lshlrev_b32_e32 v214, 16, v191
	v_and_b32_e32 v215, 0xffff0000, v191
	v_mul_f32_e32 v212, v138, v213
	v_mul_f32_e32 v213, v138, v212
	v_pk_mul_f32 v[214:215], v[212:213], v[214:215]
	v_cvt_pk_bf16_f32 v191, v214, v215
	v_lshlrev_b32_e32 v214, 16, v192
	v_and_b32_e32 v215, 0xffff0000, v192
	v_mul_f32_e32 v212, v138, v213
	v_mul_f32_e32 v213, v138, v212
	v_pk_mul_f32 v[214:215], v[212:213], v[214:215]
	v_cvt_pk_bf16_f32 v192, v214, v215
	v_lshlrev_b32_e32 v214, 16, v193
	v_and_b32_e32 v215, 0xffff0000, v193
	v_mul_f32_e32 v212, v138, v213
	v_mul_f32_e32 v213, v138, v212
	v_pk_mul_f32 v[214:215], v[212:213], v[214:215]
	v_cvt_pk_bf16_f32 v193, v214, v215
	s_nop 1
	s_waitcnt lgkmcnt(6)
	v_mfma_f32_32x32x16_bf16 v[48:63], v[190:193], v[228:231], v[48:63]
	s_waitcnt lgkmcnt(4)
	v_mfma_f32_32x32x16_bf16 v[32:47], v[190:193], v[232:235], v[32:47]
	s_waitcnt lgkmcnt(2)
	v_mfma_f32_32x32x16_bf16 v[16:31], v[190:193], v[236:239], v[16:31]
	s_waitcnt lgkmcnt(0)
	v_mfma_f32_32x32x16_bf16 v[0:15], v[190:193], v[216:219], v[0:15]
	s_add_i32 s75, s75, 1
	s_add_i32 s76, s76, 64
	s_add_i32 s77, s77, 0xc000
	s_add_u32 s42, s42, 0x40000
	s_addc_u32 s43, s43, 0
	s_add_i32 s78, s78, 1
	s_cmp_lg_u32 s77, 0x150000
	s_cbranch_scc0 .LBB0_577
